# P6 tail: FFN2 gate/up weight conversion replaced by the hand-written software-pipelined loop (next item's loads in flight during the current item's transpose/convert/store)
# speedup vs baseline: 1.0241x; 1.0011x over previous
.LBB0_878:
	v_mov_b32_e32 v0, v252
	s_waitcnt lgkmcnt(0)
	s_barrier
	s_nop 0
	v_readfirstlane_b32 s2, v0
	s_ashr_i32 s2, s2, 6
	s_add_i32 s8, s2, s79
	s_cmpk_gt_i32 s8, 0x2bff
	s_cbranch_scc1 .LBB0_892
	s_movk_i32 s72, 0x7fff
	s_mov_b32 s73, 0xffff0000
.Lmy_cvgu6:
	v_and_b32_e32 v172, 63, v252
	v_lshrrev_b32_e32 v173, 5, v172
	v_and_b32_e32 v174, 31, v172
	v_mul_u32_u24_e32 v175, 0x1600, v173
	v_add_lshl_u32 v176, v175, v174, 2
	v_lshrrev_b32_e32 v175, 6, v252
	s_nop 0
	v_readfirstlane_b32 s21, v175
	v_readlane_b32 s20, v253, 0
	s_mul_i32 s100, s21, 0x2100
	s_lshl_b32 s20, s20, 3
	s_add_u32 s20, s20, s21
	v_mul_u32_u24_e32 v175, 33, v173
	v_add_u32_e32 v175, v175, v174
	v_lshl_add_u32 v177, v175, 2, s100
	v_and_b32_e32 v173, 7, v172
	v_lshrrev_b32_e32 v174, 3, v172
	v_mul_u32_u24_e32 v175, 0x108, v173
	v_add_u32_e32 v175, v175, v174
	v_lshl_add_u32 v178, v175, 2, s100
	v_lshlrev_b32_e32 v175, 4, v173
	v_lshl_add_u32 v163, v174, 12, v175
	s_cmp_ge_u32 s20, 0x1600
	s_cselect_b32 s100, 0x1600, 0
	s_cselect_b32 s101, 49, 47
	s_cselect_b32 vcc_hi, 0x80, 0
	s_sub_u32 s100, s20, s100
	s_mul_i32 s21, s100, 0xba2f
	s_lshr_b32 s21, s21, 23
	s_mul_i32 vcc_lo, s21, 0xb0
	s_sub_u32 vcc_lo, s100, vcc_lo
	v_readlane_b32 s42, v253, s101
	s_add_u32 s101, s101, 1
	v_readlane_b32 s43, v253, s101
	v_readlane_b32 s98, v253, 45
	v_readlane_b32 s99, v253, 46
	v_readlane_b32 s54, v253, 63
	v_readlane_b32 s55, v254, 0
	s_mul_i32 s100, s21, 0x160000
	s_add_u32 s42, s42, s100
	s_addc_u32 s43, s43, 0
	s_lshl_b32 s100, vcc_lo, 7
	s_add_u32 s42, s42, s100
	s_addc_u32 s43, s43, 0
	s_lshl_b32 s100, s21, 8
	s_add_u32 s98, s98, s100
	s_addc_u32 s99, s99, 0
	s_lshr_b32 s100, vcc_lo, 2
	s_lshl_b32 s100, s100, 8
	s_and_b32 s101, vcc_lo, 3
	s_lshl_b32 s101, s101, 5
	s_add_u32 s100, s100, s101
	s_add_u32 s100, s100, vcc_hi
	s_lshl_b32 s100, s100, 12
	s_lshl_b32 s101, s21, 7
	s_add_u32 s100, s100, s101
	s_add_u32 s54, s54, s100
	s_addc_u32 s55, s55, 0
	s_add_u32 s54, s54, 0x2700000
	s_addc_u32 s55, s55, 0
	v_and_b32_e32 v172, 0x70, v163
	v_lshlrev_b32_e32 v172, 1, v172
	global_load_dwordx4 v[244:247], v172, s[98:99]
	global_load_dwordx4 v[248:251], v172, s[98:99] offset:16
	global_load_dword v180, v176, s[42:43] nt
	s_add_u32 s42, s42, 0xb000
	s_addc_u32 s43, s43, 0
	global_load_dword v181, v176, s[42:43] nt
	s_add_u32 s42, s42, 0xb000
	s_addc_u32 s43, s43, 0
	global_load_dword v182, v176, s[42:43] nt
	s_add_u32 s42, s42, 0xb000
	s_addc_u32 s43, s43, 0
	global_load_dword v183, v176, s[42:43] nt
	s_add_u32 s42, s42, 0xb000
	s_addc_u32 s43, s43, 0
	global_load_dword v184, v176, s[42:43] nt
	s_add_u32 s42, s42, 0xb000
	s_addc_u32 s43, s43, 0
	global_load_dword v185, v176, s[42:43] nt
	s_add_u32 s42, s42, 0xb000
	s_addc_u32 s43, s43, 0
	global_load_dword v186, v176, s[42:43] nt
	s_add_u32 s42, s42, 0xb000
	s_addc_u32 s43, s43, 0
	global_load_dword v187, v176, s[42:43] nt
	s_add_u32 s42, s42, 0xb000
	s_addc_u32 s43, s43, 0
	global_load_dword v188, v176, s[42:43] nt
	s_add_u32 s42, s42, 0xb000
	s_addc_u32 s43, s43, 0
	global_load_dword v189, v176, s[42:43] nt
	s_add_u32 s42, s42, 0xb000
	s_addc_u32 s43, s43, 0
	global_load_dword v190, v176, s[42:43] nt
	s_add_u32 s42, s42, 0xb000
	s_addc_u32 s43, s43, 0
	global_load_dword v191, v176, s[42:43] nt
	s_add_u32 s42, s42, 0xb000
	s_addc_u32 s43, s43, 0
	global_load_dword v192, v176, s[42:43] nt
	s_add_u32 s42, s42, 0xb000
	s_addc_u32 s43, s43, 0
	global_load_dword v193, v176, s[42:43] nt
	s_add_u32 s42, s42, 0xb000
	s_addc_u32 s43, s43, 0
	global_load_dword v194, v176, s[42:43] nt
	s_add_u32 s42, s42, 0xb000
	s_addc_u32 s43, s43, 0
	global_load_dword v195, v176, s[42:43] nt
	s_add_u32 s42, s42, 0xb000
	s_addc_u32 s43, s43, 0
	global_load_dword v196, v176, s[42:43] nt
	s_add_u32 s42, s42, 0xb000
	s_addc_u32 s43, s43, 0
	global_load_dword v197, v176, s[42:43] nt
	s_add_u32 s42, s42, 0xb000
	s_addc_u32 s43, s43, 0
	global_load_dword v198, v176, s[42:43] nt
	s_add_u32 s42, s42, 0xb000
	s_addc_u32 s43, s43, 0
	global_load_dword v199, v176, s[42:43] nt
	s_add_u32 s42, s42, 0xb000
	s_addc_u32 s43, s43, 0
	global_load_dword v200, v176, s[42:43] nt
	s_add_u32 s42, s42, 0xb000
	s_addc_u32 s43, s43, 0
	global_load_dword v201, v176, s[42:43] nt
	s_add_u32 s42, s42, 0xb000
	s_addc_u32 s43, s43, 0
	global_load_dword v202, v176, s[42:43] nt
	s_add_u32 s42, s42, 0xb000
	s_addc_u32 s43, s43, 0
	global_load_dword v203, v176, s[42:43] nt
	s_add_u32 s42, s42, 0xb000
	s_addc_u32 s43, s43, 0
	global_load_dword v204, v176, s[42:43] nt
	s_add_u32 s42, s42, 0xb000
	s_addc_u32 s43, s43, 0
	global_load_dword v205, v176, s[42:43] nt
	s_add_u32 s42, s42, 0xb000
	s_addc_u32 s43, s43, 0
	global_load_dword v206, v176, s[42:43] nt
	s_add_u32 s42, s42, 0xb000
	s_addc_u32 s43, s43, 0
	global_load_dword v207, v176, s[42:43] nt
	s_add_u32 s42, s42, 0xb000
	s_addc_u32 s43, s43, 0
	global_load_dword v208, v176, s[42:43] nt
	s_add_u32 s42, s42, 0xb000
	s_addc_u32 s43, s43, 0
	global_load_dword v209, v176, s[42:43] nt
	s_add_u32 s42, s42, 0xb000
	s_addc_u32 s43, s43, 0
	global_load_dword v210, v176, s[42:43] nt
	s_add_u32 s42, s42, 0xb000
	s_addc_u32 s43, s43, 0
	global_load_dword v211, v176, s[42:43] nt
	s_waitcnt vmcnt(0)
	s_branch .Lmy_cvgu6_body

.Lmy_cvgu6_body:
	s_mov_b64 s[44:45], s[54:55]
	ds_write_b32 v177, v180 offset:0
	ds_write_b32 v177, v181 offset:264
	ds_write_b32 v177, v182 offset:528
	ds_write_b32 v177, v183 offset:792
	ds_write_b32 v177, v184 offset:1056
	ds_write_b32 v177, v185 offset:1320
	ds_write_b32 v177, v186 offset:1584
	ds_write_b32 v177, v187 offset:1848
	ds_write_b32 v177, v188 offset:2112
	ds_write_b32 v177, v189 offset:2376
	ds_write_b32 v177, v190 offset:2640
	ds_write_b32 v177, v191 offset:2904
	ds_write_b32 v177, v192 offset:3168
	ds_write_b32 v177, v193 offset:3432
	ds_write_b32 v177, v194 offset:3696
	ds_write_b32 v177, v195 offset:3960
	ds_write_b32 v177, v196 offset:4224
	ds_write_b32 v177, v197 offset:4488
	ds_write_b32 v177, v198 offset:4752
	ds_write_b32 v177, v199 offset:5016
	ds_write_b32 v177, v200 offset:5280
	ds_write_b32 v177, v201 offset:5544
	ds_write_b32 v177, v202 offset:5808
	ds_write_b32 v177, v203 offset:6072
	ds_write_b32 v177, v204 offset:6336
	ds_write_b32 v177, v205 offset:6600
	ds_write_b32 v177, v206 offset:6864
	ds_write_b32 v177, v207 offset:7128
	ds_write_b32 v177, v208 offset:7392
	ds_write_b32 v177, v209 offset:7656
	ds_write_b32 v177, v210 offset:7920
	ds_write_b32 v177, v211 offset:8184
	v_mov_b64_e32 v[164:165], v[244:245]
	v_mov_b64_e32 v[166:167], v[246:247]
	v_mov_b64_e32 v[168:169], v[248:249]
	v_mov_b64_e32 v[170:171], v[250:251]
	s_add_u32 s20, s20, 0x800
	s_cmp_lt_u32 s20, 0x2c00
	s_cbranch_scc0 .Lmy_cvgu6_nonext
	s_cmp_ge_u32 s20, 0x1600
	s_cselect_b32 s100, 0x1600, 0
	s_cselect_b32 s101, 49, 47
	s_cselect_b32 vcc_hi, 0x80, 0
	s_sub_u32 s100, s20, s100
	s_mul_i32 s21, s100, 0xba2f
	s_lshr_b32 s21, s21, 23
	s_mul_i32 vcc_lo, s21, 0xb0
	s_sub_u32 vcc_lo, s100, vcc_lo
	v_readlane_b32 s42, v253, s101
	s_add_u32 s101, s101, 1
	v_readlane_b32 s43, v253, s101
	v_readlane_b32 s98, v253, 45
	v_readlane_b32 s99, v253, 46
	v_readlane_b32 s54, v253, 63
	v_readlane_b32 s55, v254, 0
	s_mul_i32 s100, s21, 0x160000
	s_add_u32 s42, s42, s100
	s_addc_u32 s43, s43, 0
	s_lshl_b32 s100, vcc_lo, 7
	s_add_u32 s42, s42, s100
	s_addc_u32 s43, s43, 0
	s_lshl_b32 s100, s21, 8
	s_add_u32 s98, s98, s100
	s_addc_u32 s99, s99, 0
	s_lshr_b32 s100, vcc_lo, 2
	s_lshl_b32 s100, s100, 8
	s_and_b32 s101, vcc_lo, 3
	s_lshl_b32 s101, s101, 5
	s_add_u32 s100, s100, s101
	s_add_u32 s100, s100, vcc_hi
	s_lshl_b32 s100, s100, 12
	s_lshl_b32 s101, s21, 7
	s_add_u32 s100, s100, s101
	s_add_u32 s54, s54, s100
	s_addc_u32 s55, s55, 0
	s_add_u32 s54, s54, 0x2700000
	s_addc_u32 s55, s55, 0
	v_and_b32_e32 v172, 0x70, v163
	v_lshlrev_b32_e32 v172, 1, v172
	global_load_dwordx4 v[244:247], v172, s[98:99]
	global_load_dwordx4 v[248:251], v172, s[98:99] offset:16
	global_load_dword v180, v176, s[42:43] nt
	s_add_u32 s42, s42, 0xb000
	s_addc_u32 s43, s43, 0
	global_load_dword v181, v176, s[42:43] nt
	s_add_u32 s42, s42, 0xb000
	s_addc_u32 s43, s43, 0
	global_load_dword v182, v176, s[42:43] nt
	s_add_u32 s42, s42, 0xb000
	s_addc_u32 s43, s43, 0
	global_load_dword v183, v176, s[42:43] nt
	s_add_u32 s42, s42, 0xb000
	s_addc_u32 s43, s43, 0
	global_load_dword v184, v176, s[42:43] nt
	s_add_u32 s42, s42, 0xb000
	s_addc_u32 s43, s43, 0
	global_load_dword v185, v176, s[42:43] nt
	s_add_u32 s42, s42, 0xb000
	s_addc_u32 s43, s43, 0
	global_load_dword v186, v176, s[42:43] nt
	s_add_u32 s42, s42, 0xb000
	s_addc_u32 s43, s43, 0
	global_load_dword v187, v176, s[42:43] nt
	s_add_u32 s42, s42, 0xb000
	s_addc_u32 s43, s43, 0
	global_load_dword v188, v176, s[42:43] nt
	s_add_u32 s42, s42, 0xb000
	s_addc_u32 s43, s43, 0
	global_load_dword v189, v176, s[42:43] nt
	s_add_u32 s42, s42, 0xb000
	s_addc_u32 s43, s43, 0
	global_load_dword v190, v176, s[42:43] nt
	s_add_u32 s42, s42, 0xb000
	s_addc_u32 s43, s43, 0
	global_load_dword v191, v176, s[42:43] nt
	s_add_u32 s42, s42, 0xb000
	s_addc_u32 s43, s43, 0
	global_load_dword v192, v176, s[42:43] nt
	s_add_u32 s42, s42, 0xb000
	s_addc_u32 s43, s43, 0
	global_load_dword v193, v176, s[42:43] nt
	s_add_u32 s42, s42, 0xb000
	s_addc_u32 s43, s43, 0
	global_load_dword v194, v176, s[42:43] nt
	s_add_u32 s42, s42, 0xb000
	s_addc_u32 s43, s43, 0
	global_load_dword v195, v176, s[42:43] nt
	s_add_u32 s42, s42, 0xb000
	s_addc_u32 s43, s43, 0
	global_load_dword v196, v176, s[42:43] nt
	s_add_u32 s42, s42, 0xb000
	s_addc_u32 s43, s43, 0
	global_load_dword v197, v176, s[42:43] nt
	s_add_u32 s42, s42, 0xb000
	s_addc_u32 s43, s43, 0
	global_load_dword v198, v176, s[42:43] nt
	s_add_u32 s42, s42, 0xb000
	s_addc_u32 s43, s43, 0
	global_load_dword v199, v176, s[42:43] nt
	s_add_u32 s42, s42, 0xb000
	s_addc_u32 s43, s43, 0
	global_load_dword v200, v176, s[42:43] nt
	s_add_u32 s42, s42, 0xb000
	s_addc_u32 s43, s43, 0
	global_load_dword v201, v176, s[42:43] nt
	s_add_u32 s42, s42, 0xb000
	s_addc_u32 s43, s43, 0
	global_load_dword v202, v176, s[42:43] nt
	s_add_u32 s42, s42, 0xb000
	s_addc_u32 s43, s43, 0
	global_load_dword v203, v176, s[42:43] nt
	s_add_u32 s42, s42, 0xb000
	s_addc_u32 s43, s43, 0
	global_load_dword v204, v176, s[42:43] nt
	s_add_u32 s42, s42, 0xb000
	s_addc_u32 s43, s43, 0
	global_load_dword v205, v176, s[42:43] nt
	s_add_u32 s42, s42, 0xb000
	s_addc_u32 s43, s43, 0
	global_load_dword v206, v176, s[42:43] nt
	s_add_u32 s42, s42, 0xb000
	s_addc_u32 s43, s43, 0
	global_load_dword v207, v176, s[42:43] nt
	s_add_u32 s42, s42, 0xb000
	s_addc_u32 s43, s43, 0
	global_load_dword v208, v176, s[42:43] nt
	s_add_u32 s42, s42, 0xb000
	s_addc_u32 s43, s43, 0
	global_load_dword v209, v176, s[42:43] nt
	s_add_u32 s42, s42, 0xb000
	s_addc_u32 s43, s43, 0
	global_load_dword v210, v176, s[42:43] nt
	s_add_u32 s42, s42, 0xb000
	s_addc_u32 s43, s43, 0
	global_load_dword v211, v176, s[42:43] nt
.Lmy_cvgu6_nonext:
	s_waitcnt lgkmcnt(0)
	ds_read2_b32 v[212:213], v178 offset0:0 offset1:33
	ds_read2_b32 v[214:215], v178 offset0:66 offset1:99
	ds_read2_b32 v[216:217], v178 offset0:132 offset1:165
	ds_read2_b32 v[218:219], v178 offset0:198 offset1:231
	ds_read2_b32 v[220:221], v178 offset0:8 offset1:41
	ds_read2_b32 v[222:223], v178 offset0:74 offset1:107
	ds_read2_b32 v[224:225], v178 offset0:140 offset1:173
	ds_read2_b32 v[226:227], v178 offset0:206 offset1:239
	ds_read2_b32 v[228:229], v178 offset0:16 offset1:49
	ds_read2_b32 v[230:231], v178 offset0:82 offset1:115
	ds_read2_b32 v[232:233], v178 offset0:148 offset1:181
	ds_read2_b32 v[234:235], v178 offset0:214 offset1:247
	s_waitcnt lgkmcnt(8)
	v_pk_mul_f32 v[212:213], v[212:213], v[164:165]
	v_pk_mul_f32 v[214:215], v[214:215], v[166:167]
	v_pk_mul_f32 v[216:217], v[216:217], v[168:169]
	v_pk_mul_f32 v[218:219], v[218:219], v[170:171]
	v_bfe_u32 v172, v212, 16, 1
	v_bfe_u32 v173, v213, 16, 1
	v_add3_u32 v172, v212, v172, s72
	v_add3_u32 v173, v213, v173, s72
	v_lshrrev_b32_e32 v172, 16, v172
	v_and_or_b32 v212, v173, s73, v172
	v_bfe_u32 v172, v214, 16, 1
	v_bfe_u32 v173, v215, 16, 1
	v_add3_u32 v172, v214, v172, s72
	v_add3_u32 v173, v215, v173, s72
	v_lshrrev_b32_e32 v172, 16, v172
	v_and_or_b32 v213, v173, s73, v172
	v_bfe_u32 v172, v216, 16, 1
	v_bfe_u32 v173, v217, 16, 1
	v_add3_u32 v172, v216, v172, s72
	v_add3_u32 v173, v217, v173, s72
	v_lshrrev_b32_e32 v172, 16, v172
	v_and_or_b32 v214, v173, s73, v172
	v_bfe_u32 v172, v218, 16, 1
	v_bfe_u32 v173, v219, 16, 1
	v_add3_u32 v172, v218, v172, s72
	v_add3_u32 v173, v219, v173, s72
	v_lshrrev_b32_e32 v172, 16, v172
	v_and_or_b32 v215, v173, s73, v172
	global_store_dwordx4 v163, v[212:215], s[44:45]
	s_add_u32 s44, s44, 0x8000
	s_addc_u32 s45, s45, 0
	ds_read2_b32 v[236:237], v178 offset0:24 offset1:57
	ds_read2_b32 v[238:239], v178 offset0:90 offset1:123
	ds_read2_b32 v[240:241], v178 offset0:156 offset1:189
	ds_read2_b32 v[242:243], v178 offset0:222 offset1:255
	s_waitcnt lgkmcnt(8)
	v_pk_mul_f32 v[220:221], v[220:221], v[164:165]
	v_pk_mul_f32 v[222:223], v[222:223], v[166:167]
	v_pk_mul_f32 v[224:225], v[224:225], v[168:169]
	v_pk_mul_f32 v[226:227], v[226:227], v[170:171]
	v_bfe_u32 v172, v220, 16, 1
	v_bfe_u32 v173, v221, 16, 1
	v_add3_u32 v172, v220, v172, s72
	v_add3_u32 v173, v221, v173, s72
	v_lshrrev_b32_e32 v172, 16, v172
	v_and_or_b32 v220, v173, s73, v172
	v_bfe_u32 v172, v222, 16, 1
	v_bfe_u32 v173, v223, 16, 1
	v_add3_u32 v172, v222, v172, s72
	v_add3_u32 v173, v223, v173, s72
	v_lshrrev_b32_e32 v172, 16, v172
	v_and_or_b32 v221, v173, s73, v172
	v_bfe_u32 v172, v224, 16, 1
	v_bfe_u32 v173, v225, 16, 1
	v_add3_u32 v172, v224, v172, s72
	v_add3_u32 v173, v225, v173, s72
	v_lshrrev_b32_e32 v172, 16, v172
	v_and_or_b32 v222, v173, s73, v172
	v_bfe_u32 v172, v226, 16, 1
	v_bfe_u32 v173, v227, 16, 1
	v_add3_u32 v172, v226, v172, s72
	v_add3_u32 v173, v227, v173, s72
	v_lshrrev_b32_e32 v172, 16, v172
	v_and_or_b32 v223, v173, s73, v172
	global_store_dwordx4 v163, v[220:223], s[44:45]
	s_add_u32 s44, s44, 0x8000
	s_addc_u32 s45, s45, 0
	s_waitcnt lgkmcnt(4)
	v_pk_mul_f32 v[228:229], v[228:229], v[164:165]
	v_pk_mul_f32 v[230:231], v[230:231], v[166:167]
	v_pk_mul_f32 v[232:233], v[232:233], v[168:169]
	v_pk_mul_f32 v[234:235], v[234:235], v[170:171]
	v_bfe_u32 v172, v228, 16, 1
	v_bfe_u32 v173, v229, 16, 1
	v_add3_u32 v172, v228, v172, s72
	v_add3_u32 v173, v229, v173, s72
	v_lshrrev_b32_e32 v172, 16, v172
	v_and_or_b32 v228, v173, s73, v172
	v_bfe_u32 v172, v230, 16, 1
	v_bfe_u32 v173, v231, 16, 1
	v_add3_u32 v172, v230, v172, s72
	v_add3_u32 v173, v231, v173, s72
	v_lshrrev_b32_e32 v172, 16, v172
	v_and_or_b32 v229, v173, s73, v172
	v_bfe_u32 v172, v232, 16, 1
	v_bfe_u32 v173, v233, 16, 1
	v_add3_u32 v172, v232, v172, s72
	v_add3_u32 v173, v233, v173, s72
	v_lshrrev_b32_e32 v172, 16, v172
	v_and_or_b32 v230, v173, s73, v172
	v_bfe_u32 v172, v234, 16, 1
	v_bfe_u32 v173, v235, 16, 1
	v_add3_u32 v172, v234, v172, s72
	v_add3_u32 v173, v235, v173, s72
	v_lshrrev_b32_e32 v172, 16, v172
	v_and_or_b32 v231, v173, s73, v172
	global_store_dwordx4 v163, v[228:231], s[44:45]
	s_add_u32 s44, s44, 0x8000
	s_addc_u32 s45, s45, 0
	s_waitcnt lgkmcnt(0)
	v_pk_mul_f32 v[236:237], v[236:237], v[164:165]
	v_pk_mul_f32 v[238:239], v[238:239], v[166:167]
	v_pk_mul_f32 v[240:241], v[240:241], v[168:169]
	v_pk_mul_f32 v[242:243], v[242:243], v[170:171]
	v_bfe_u32 v172, v236, 16, 1
	v_bfe_u32 v173, v237, 16, 1
	v_add3_u32 v172, v236, v172, s72
	v_add3_u32 v173, v237, v173, s72
	v_lshrrev_b32_e32 v172, 16, v172
	v_and_or_b32 v236, v173, s73, v172
	v_bfe_u32 v172, v238, 16, 1
	v_bfe_u32 v173, v239, 16, 1
	v_add3_u32 v172, v238, v172, s72
	v_add3_u32 v173, v239, v173, s72
	v_lshrrev_b32_e32 v172, 16, v172
	v_and_or_b32 v237, v173, s73, v172
	v_bfe_u32 v172, v240, 16, 1
	v_bfe_u32 v173, v241, 16, 1
	v_add3_u32 v172, v240, v172, s72
	v_add3_u32 v173, v241, v173, s72
	v_lshrrev_b32_e32 v172, 16, v172
	v_and_or_b32 v238, v173, s73, v172
	v_bfe_u32 v172, v242, 16, 1
	v_bfe_u32 v173, v243, 16, 1
	v_add3_u32 v172, v242, v172, s72
	v_add3_u32 v173, v243, v173, s72
	v_lshrrev_b32_e32 v172, 16, v172
	v_and_or_b32 v239, v173, s73, v172
	global_store_dwordx4 v163, v[236:239], s[44:45]
	s_cmp_lt_u32 s20, 0x2c00
	s_cbranch_scc1 .Lmy_cvgu6_top
